# v61 + s5 gelu: the three consecutive constant multiplies (0.79788, -2, log2e) folded into one constant (31 sites; fewer roundings)
# baseline (speedup 1.0000x reference)
; #define LAS __attribute__((address_space(3)))
; __device__ __forceinline__ unsigned pk2(float lo, float hi) { unsigned r; asm("v_cvt_pk_bf16_f32 %0, %1, %2" : "=v"(r) : "v"(lo), "v"(hi)); return r; }
; __device__ __forceinline__ void lds_fence() { asm volatile("s_waitcnt lgkmcnt(0)" ::: "memory"); }
; __device__ __forceinline__ f32x4 mfma16(bf16x8 a, bf16x8 b, f32x4 c) { return __builtin_amdgcn_mfma_f32_16x16x32_bf16(a, b, c, 0, 0, 0); }
; template <int PASS>
; __device__ __forceinline__ void s5_pass(CArgs& a, LAS unsigned char* lds, int l, int panel) {
;     ...
;         for (int nt = 0; nt < 4; ++nt) {
;             bf16x8 xf[2];
; #pragma unroll
;             for (int ks = 0; ks < 2; ++ks) xf[ks] = *(const bf16x8*)(Zp + (size_t)(64 * nt + 4 * fr + 2 * ks + (fq >> 1)) * ZROWB + (C_S5U + g * 16 + (fq & 1) * 8) * 2);
; #pragma unroll
;             for (int mt = 0; mt < 8; ++mt) {
;                 f32x4 acc = mfma16(wf[mt][0], xf[0], (f32x4){0.f, 0.f, 0.f, 0.f});
;                 acc = mfma16(wf[mt][1], xf[1], acc);
;                 *(LAS f32x4*)(hl + fr * 128 + 16 * mt + 4 * fq) = acc;
;             }
;             lds_fence();
;             for (int j = 0; j < 16; ++j) {
;                 if (PASS == 2) *(LAS unsigned*)(xh + j * 128 + 2 * lane) = pk2(Hr, Hi);
;                 const f32x2 lc = *(LAS f32x2*)(hl + j * 128 + 2 * lane);
;                 const float nr = a4r * Hr - a4i * Hi + lc.x, ni = a4r * Hi + a4i * Hr + lc.y;
;                 Hr = nr; Hi = ni;
;             }
.LBB0_363:
	v_lshl_add_u64 v[136:137], v[208:209], 0, s[88:89]
	v_add_co_u32_e32 v138, vcc, 0xe000000, v136
	v_add_u32_e32 v241, v239, v173
	s_nop 0
	v_addc_co_u32_e32 v139, vcc, 0, v137, vcc
	global_load_dwordx4 v[138:141], v[138:139], off
	v_add_co_u32_e32 v136, vcc, 0xe002000, v136
	s_waitcnt vmcnt(1)
	v_mul_f32_e32 v150, v201, v135
	v_addc_co_u32_e32 v137, vcc, 0, v137, vcc
	global_load_dwordx4 v[142:145], v[136:137], off offset:2048
	v_mul_f32_e32 v136, v197, v135
	v_cvt_pk_bf16_f32 v151, v134, v135
	v_pk_fma_f32 v[136:137], v[196:197], v[134:135], v[136:137] op_sel_hi:[1,1,0] neg_lo:[0,0,1] neg_hi:[0,0,1]
	v_pk_fma_f32 v[134:135], v[200:201], v[134:135], v[150:151] op_sel_hi:[1,1,0]
	v_lshl_add_u64 v[214:215], v[210:211], 0, s[88:89]
	v_add_co_u32_e32 v216, vcc, s20, v214
	s_add_i32 s8, s8, -1
	s_nop 0
	v_addc_co_u32_e32 v217, vcc, 0, v215, vcc
	v_add_co_u32_e32 v244, vcc, s95, v214
	v_lshl_add_u64 v[208:209], v[208:209], 0, s[82:83]
	s_nop 0
	v_addc_co_u32_e32 v245, vcc, 0, v215, vcc
	v_lshl_add_u64 v[210:211], v[210:211], 0, s[82:83]
	s_cmp_lg_u32 s8, 0
	global_load_dwordx2 v[218:219], v[216:217], off
	global_load_dwordx2 v[224:225], v[244:245], off offset:1024
	v_add_co_u32_e32 v246, vcc, s0, v214
	s_nop 1
	v_addc_co_u32_e32 v247, vcc, 0, v215, vcc
	global_load_dwordx2 v[254:255], v[246:247], off offset:2048
	v_add_co_u32_e32 v246, vcc, s96, v214
	s_nop 1
	v_addc_co_u32_e32 v247, vcc, 0, v215, vcc
	global_load_dword v223, v[246:247], off offset:3072
	global_load_dword v226, v[246:247], off offset:3076
	s_waitcnt vmcnt(6)
	v_mfma_f32_16x16x32_bf16 v[146:149], v[2:5], v[138:141], 0
	s_waitcnt vmcnt(5)
	v_mfma_f32_16x16x32_bf16 v[146:149], v[6:9], v[142:145], v[146:149]
	s_nop 7
	ds_write_b128 v238, v[146:149]
	v_mfma_f32_16x16x32_bf16 v[146:149], v[10:13], v[138:141], 0
	v_mfma_f32_16x16x32_bf16 v[146:149], v[14:17], v[142:145], v[146:149]
	s_nop 7
	ds_write_b128 v238, v[146:149] offset:64
	v_mfma_f32_16x16x32_bf16 v[146:149], v[18:21], v[138:141], 0
	v_mfma_f32_16x16x32_bf16 v[146:149], v[22:25], v[142:145], v[146:149]
	s_nop 7
	ds_write_b128 v238, v[146:149] offset:128
	v_mfma_f32_16x16x32_bf16 v[146:149], v[26:29], v[138:141], 0
	v_mfma_f32_16x16x32_bf16 v[146:149], v[30:33], v[142:145], v[146:149]
	s_nop 7
	ds_write_b128 v238, v[146:149] offset:192
	v_mfma_f32_16x16x32_bf16 v[146:149], v[34:37], v[138:141], 0
	v_mfma_f32_16x16x32_bf16 v[146:149], v[38:41], v[142:145], v[146:149]
	s_nop 7
	ds_write_b128 v238, v[146:149] offset:256
	v_mfma_f32_16x16x32_bf16 v[146:149], v[42:45], v[138:141], 0
	v_mfma_f32_16x16x32_bf16 v[146:149], v[46:49], v[142:145], v[146:149]
	s_nop 7
	ds_write_b128 v238, v[146:149] offset:320
	v_mfma_f32_16x16x32_bf16 v[146:149], v[50:53], v[138:141], 0
	v_mfma_f32_16x16x32_bf16 v[146:149], v[54:57], v[142:145], v[146:149]
	s_nop 7
	ds_write_b128 v238, v[146:149] offset:384
	v_mfma_f32_16x16x32_bf16 v[146:149], v[58:61], v[138:141], 0
	v_mfma_f32_16x16x32_bf16 v[146:149], v[62:65], v[142:145], v[146:149]
	s_nop 7
	ds_write_b128 v238, v[146:149] offset:448
	s_waitcnt lgkmcnt(0)
	ds_read2st64_b64 v[146:149], v241 offset1:1
	s_waitcnt lgkmcnt(0)
	v_pk_add_f32 v[134:135], v[134:135], v[146:147] op_sel:[0,1] op_sel_hi:[1,0]
	v_pk_add_f32 v[136:137], v[136:137], v[146:147]
	s_nop 0
	v_cvt_pk_bf16_f32 v146, v136, v134
	v_pk_mul_f32 v[134:135], v[200:201], v[134:135] op_sel_hi:[1,0]
	ds_write2st64_b32 v239, v151, v146 offset0:32 offset1:33
	v_pk_fma_f32 v[146:147], v[196:197], v[136:137], v[134:135] neg_lo:[0,0,1] neg_hi:[0,0,1]
	v_pk_fma_f32 v[134:135], v[196:197], v[136:137], v[134:135] op_sel_hi:[1,0,1]
	s_nop 0
	v_mov_b32_e32 v147, v135
	ds_read2st64_b64 v[134:137], v241 offset0:2 offset1:3
	v_pk_add_f32 v[146:147], v[146:147], v[148:149]
	s_nop 0
	v_mul_f32_e32 v148, v197, v147
	v_mul_f32_e32 v150, v197, v146
	v_cvt_pk_bf16_f32 v151, v146, v147
	v_pk_fma_f32 v[148:149], v[196:197], v[146:147], v[148:149] op_sel_hi:[1,1,0] neg_lo:[0,0,1] neg_hi:[0,0,1]
	v_pk_fma_f32 v[146:147], v[196:197], v[146:147], v[150:151] op_sel:[0,1,0] op_sel_hi:[1,0,0]
	s_waitcnt lgkmcnt(0)
	v_pk_add_f32 v[148:149], v[148:149], v[134:135]
	v_pk_add_f32 v[134:135], v[146:147], v[134:135] op_sel:[0,1] op_sel_hi:[1,0]
	s_nop 0
	v_cvt_pk_bf16_f32 v146, v148, v134
	v_pk_mul_f32 v[134:135], v[200:201], v[134:135] op_sel_hi:[1,0]
	ds_write2st64_b32 v239, v151, v146 offset0:34 offset1:35
	v_pk_fma_f32 v[146:147], v[196:197], v[148:149], v[134:135] neg_lo:[0,0,1] neg_hi:[0,0,1]
	v_pk_fma_f32 v[134:135], v[196:197], v[148:149], v[134:135] op_sel_hi:[1,0,1]
	s_nop 0
	v_mov_b32_e32 v147, v135
	v_pk_add_f32 v[146:147], v[146:147], v[136:137]
	ds_read2st64_b64 v[134:137], v241 offset0:4 offset1:5
	v_mul_f32_e32 v148, v197, v147
	v_mul_f32_e32 v150, v197, v146
	v_cvt_pk_bf16_f32 v151, v146, v147
	v_pk_fma_f32 v[148:149], v[196:197], v[146:147], v[148:149] op_sel_hi:[1,1,0] neg_lo:[0,0,1] neg_hi:[0,0,1]
	v_pk_fma_f32 v[146:147], v[196:197], v[146:147], v[150:151] op_sel:[0,1,0] op_sel_hi:[1,0,0]
	s_waitcnt lgkmcnt(0)
	v_pk_add_f32 v[148:149], v[148:149], v[134:135]
	v_pk_add_f32 v[134:135], v[146:147], v[134:135] op_sel:[0,1] op_sel_hi:[1,0]
	s_nop 0
	v_cvt_pk_bf16_f32 v146, v148, v134
	v_pk_mul_f32 v[134:135], v[200:201], v[134:135] op_sel_hi:[1,0]
	ds_write2st64_b32 v239, v151, v146 offset0:36 offset1:37
	v_pk_fma_f32 v[146:147], v[196:197], v[148:149], v[134:135] neg_lo:[0,0,1] neg_hi:[0,0,1]
	v_pk_fma_f32 v[134:135], v[196:197], v[148:149], v[134:135] op_sel_hi:[1,0,1]
	s_nop 0
	v_mov_b32_e32 v147, v135
	v_pk_add_f32 v[146:147], v[146:147], v[136:137]
	ds_read2st64_b64 v[134:137], v241 offset0:6 offset1:7
	v_mul_f32_e32 v148, v197, v147
	v_mul_f32_e32 v150, v197, v146
	v_cvt_pk_bf16_f32 v151, v146, v147
	v_pk_fma_f32 v[148:149], v[196:197], v[146:147], v[148:149] op_sel_hi:[1,1,0] neg_lo:[0,0,1] neg_hi:[0,0,1]
	v_pk_fma_f32 v[146:147], v[196:197], v[146:147], v[150:151] op_sel:[0,1,0] op_sel_hi:[1,0,0]
	s_waitcnt lgkmcnt(0)
; #define LAS __attribute__((address_space(3)))
; __device__ __forceinline__ unsigned pk2(float lo, float hi) { unsigned r; asm("v_cvt_pk_bf16_f32 %0, %1, %2" : "=v"(r) : "v"(lo), "v"(hi)); return r; }
; __device__ __forceinline__ void lds_fence() { asm volatile("s_waitcnt lgkmcnt(0)" ::: "memory"); }
; __device__ __forceinline__ f32x4 mfma16(bf16x8 a, bf16x8 b, f32x4 c) { return __builtin_amdgcn_mfma_f32_16x16x32_bf16(a, b, c, 0, 0, 0); }
; template <int PASS>
; __device__ __forceinline__ void s5_pass(CArgs& a, LAS unsigned char* lds, int l, int panel) {
;     ...
;             for (int j = 0; j < 16; ++j) {
;                 if (PASS == 2) *(LAS unsigned*)(xh + j * 128 + 2 * lane) = pk2(Hr, Hi);
;                 const f32x2 lc = *(LAS f32x2*)(hl + j * 128 + 2 * lane);
;                 const float nr = a4r * Hr - a4i * Hi + lc.x, ni = a4r * Hi + a4i * Hr + lc.y;
;                 Hr = nr; Hi = ni;
;             }
;             lds_fence();
;             if (PASS == 2) {
;                 bf16x8 xhf[4];
; #pragma unroll
;                 for (int k4 = 0; k4 < 4; ++k4) xhf[k4] = *(const LAS bf16x8*)(xh + fr * 128 + 32 * k4 + 8 * fq);
; #pragma unroll
;                 for (int mt = 0; mt < 4; ++mt) {
;                     f32x4 acc = (f32x4){0.f, 0.f, 0.f, 0.f};
; #pragma unroll
;                     for (int ks = 0; ks < 2; ++ks) if (2 * ks <= mt) acc = mfma16(*(const bf16x8*)(Mg + (size_t)(16 * mt + fr) * 192 + 32 * ks + 8 * fq), xf[ks], acc);
; #pragma unroll
;                     for (int k4 = 0; k4 < 4; ++k4) acc = mfma16(mf[mt][k4], xhf[k4], acc);
	v_pk_add_f32 v[148:149], v[148:149], v[134:135]
	v_pk_add_f32 v[134:135], v[146:147], v[134:135] op_sel:[0,1] op_sel_hi:[1,0]
	s_nop 0
	v_cvt_pk_bf16_f32 v146, v148, v134
	v_pk_mul_f32 v[134:135], v[200:201], v[134:135] op_sel_hi:[1,0]
	ds_write2st64_b32 v239, v151, v146 offset0:38 offset1:39
	v_pk_fma_f32 v[146:147], v[196:197], v[148:149], v[134:135] neg_lo:[0,0,1] neg_hi:[0,0,1]
	v_pk_fma_f32 v[134:135], v[196:197], v[148:149], v[134:135] op_sel_hi:[1,0,1]
	s_nop 0
	v_mov_b32_e32 v147, v135
	v_pk_add_f32 v[146:147], v[146:147], v[136:137]
	ds_read2st64_b64 v[134:137], v241 offset0:8 offset1:9
	v_mul_f32_e32 v148, v197, v147
	v_mul_f32_e32 v150, v197, v146
	v_cvt_pk_bf16_f32 v151, v146, v147
	v_pk_fma_f32 v[148:149], v[196:197], v[146:147], v[148:149] op_sel_hi:[1,1,0] neg_lo:[0,0,1] neg_hi:[0,0,1]
	v_pk_fma_f32 v[146:147], v[196:197], v[146:147], v[150:151] op_sel:[0,1,0] op_sel_hi:[1,0,0]
	s_waitcnt lgkmcnt(0)
	v_pk_add_f32 v[148:149], v[148:149], v[134:135]
	v_pk_add_f32 v[134:135], v[146:147], v[134:135] op_sel:[0,1] op_sel_hi:[1,0]
	s_nop 0
	v_cvt_pk_bf16_f32 v146, v148, v134
	v_pk_mul_f32 v[134:135], v[200:201], v[134:135] op_sel_hi:[1,0]
	ds_write2st64_b32 v239, v151, v146 offset0:40 offset1:41
	v_pk_fma_f32 v[146:147], v[196:197], v[148:149], v[134:135] neg_lo:[0,0,1] neg_hi:[0,0,1]
	v_pk_fma_f32 v[134:135], v[196:197], v[148:149], v[134:135] op_sel_hi:[1,0,1]
	s_nop 0
	v_mov_b32_e32 v147, v135
	v_pk_add_f32 v[146:147], v[146:147], v[136:137]
	ds_read2st64_b64 v[134:137], v241 offset0:10 offset1:11
	v_mul_f32_e32 v148, v197, v147
	v_mul_f32_e32 v150, v197, v146
	v_cvt_pk_bf16_f32 v151, v146, v147
	v_pk_fma_f32 v[148:149], v[196:197], v[146:147], v[148:149] op_sel_hi:[1,1,0] neg_lo:[0,0,1] neg_hi:[0,0,1]
	v_pk_fma_f32 v[146:147], v[196:197], v[146:147], v[150:151] op_sel:[0,1,0] op_sel_hi:[1,0,0]
	s_waitcnt lgkmcnt(0)
	v_pk_add_f32 v[148:149], v[148:149], v[134:135]
	v_pk_add_f32 v[134:135], v[146:147], v[134:135] op_sel:[0,1] op_sel_hi:[1,0]
	s_nop 0
	v_cvt_pk_bf16_f32 v146, v148, v134
	v_pk_mul_f32 v[134:135], v[196:197], v[134:135] op_sel_hi:[1,0]
	ds_write2st64_b32 v239, v151, v146 offset0:42 offset1:43
	v_pk_fma_f32 v[146:147], v[200:201], v[148:149], v[134:135]
	v_pk_fma_f32 v[134:135], v[200:201], v[148:149], v[134:135] op_sel_hi:[1,0,1] neg_lo:[0,0,1] neg_hi:[0,0,1]
	s_nop 0
	v_mov_b32_e32 v147, v135
	v_pk_add_f32 v[146:147], v[146:147], v[136:137] op_sel:[0,1] op_sel_hi:[1,0]
	ds_read2st64_b64 v[134:137], v241 offset0:12 offset1:13
	v_mul_f32_e32 v148, v197, v146
	v_mul_f32_e32 v150, v197, v147
	v_cvt_pk_bf16_f32 v151, v147, v146
	v_pk_fma_f32 v[148:149], v[196:197], v[146:147], v[148:149] op_sel:[0,1,0] op_sel_hi:[1,0,0] neg_lo:[0,0,1] neg_hi:[0,0,1]
	v_pk_fma_f32 v[146:147], v[196:197], v[146:147], v[150:151] op_sel_hi:[1,1,0]
	s_waitcnt lgkmcnt(0)
	v_pk_add_f32 v[148:149], v[148:149], v[134:135]
	v_pk_add_f32 v[134:135], v[146:147], v[134:135] op_sel:[0,1] op_sel_hi:[1,0]
	s_nop 0
	v_cvt_pk_bf16_f32 v146, v148, v134
	v_pk_mul_f32 v[134:135], v[196:197], v[134:135] op_sel_hi:[1,0]
	ds_write2st64_b32 v239, v151, v146 offset0:44 offset1:45
	v_pk_fma_f32 v[146:147], v[200:201], v[148:149], v[134:135]
	v_pk_fma_f32 v[134:135], v[200:201], v[148:149], v[134:135] op_sel_hi:[1,0,1] neg_lo:[0,0,1] neg_hi:[0,0,1]
	s_nop 0
	v_mov_b32_e32 v147, v135
	v_pk_add_f32 v[146:147], v[146:147], v[136:137] op_sel:[0,1] op_sel_hi:[1,0]
	ds_read2st64_b64 v[134:137], v241 offset0:14 offset1:15
	v_mul_f32_e32 v148, v197, v146
	v_pk_fma_f32 v[148:149], v[196:197], v[146:147], v[148:149] op_sel:[0,1,0] op_sel_hi:[1,0,0] neg_lo:[0,0,1] neg_hi:[0,0,1]
	v_cvt_pk_bf16_f32 v150, v147, v146
	s_waitcnt lgkmcnt(0)
	v_pk_add_f32 v[162:163], v[148:149], v[134:135]
	v_mul_f32_e32 v148, v197, v147
	v_pk_fma_f32 v[146:147], v[196:197], v[146:147], v[148:149] op_sel_hi:[1,1,0]
	s_nop 0
	v_pk_add_f32 v[134:135], v[146:147], v[134:135] op_sel:[0,1] op_sel_hi:[1,0]
	s_nop 0
	v_cvt_pk_bf16_f32 v146, v162, v134
	ds_write2st64_b32 v239, v150, v146 offset0:46 offset1:47
	v_pk_mul_f32 v[164:165], v[200:201], v[134:135] op_sel_hi:[1,0]
	s_waitcnt lgkmcnt(0)
	ds_read_b128 v[146:149], v240 offset:8192
	ds_read_b128 v[150:153], v240 offset:8256
	ds_read_b128 v[154:157], v240 offset:8320
	ds_read_b128 v[158:161], v240 offset:8384
	v_pk_fma_f32 v[134:135], v[196:197], v[162:163], v[164:165] neg_lo:[0,0,1] neg_hi:[0,0,1]
	v_pk_fma_f32 v[162:163], v[196:197], v[162:163], v[164:165] op_sel_hi:[1,0,1]
	v_mov_b32_e32 v135, v163
	ds_read_b128 v[162:165], v220
	s_waitcnt vmcnt(0) lgkmcnt(0)
	v_mfma_f32_16x16x32_bf16 v[162:165], v[162:165], v[138:141], 0
	v_lshlrev_b32_e32 v177, 16, v218
	v_pk_add_f32 v[134:135], v[134:135], v[136:137]
	s_waitcnt lgkmcnt(3)
	v_mfma_f32_16x16x32_bf16 v[162:165], v[66:69], v[146:149], v[162:165]
	s_waitcnt lgkmcnt(2)
	v_mfma_f32_16x16x32_bf16 v[162:165], v[70:73], v[150:153], v[162:165]
	s_waitcnt lgkmcnt(1)
	v_mfma_f32_16x16x32_bf16 v[162:165], v[74:77], v[154:157], v[162:165]
	s_waitcnt lgkmcnt(0)
; __device__ __forceinline__ unsigned pk2(float lo, float hi) { unsigned r; asm("v_cvt_pk_bf16_f32 %0, %1, %2" : "=v"(r) : "v"(lo), "v"(hi)); return r; }
; __device__ __forceinline__ float bflo(unsigned w) { return __uint_as_float(w << 16); }
; __device__ __forceinline__ float bfhi(unsigned w) { return __uint_as_float(w & 0xffff0000u); }
; __device__ __forceinline__ float gelu_tanh(float x) { const float u = 0.7978845608028654f * (x + 0.044715f * x * x * x); return x * __builtin_amdgcn_rcpf(1.f + fexp(-2.f * u)); }
; __device__ __forceinline__ f32x4 mfma16(bf16x8 a, bf16x8 b, f32x4 c) { return __builtin_amdgcn_mfma_f32_16x16x32_bf16(a, b, c, 0, 0, 0); }
; template <int PASS>
; __device__ __forceinline__ void s5_pass(CArgs& a, LAS unsigned char* lds, int l, int panel) {
;     ...
;                     for (int ks = 0; ks < 2; ++ks) if (2 * ks <= mt) acc = mfma16(*(const bf16x8*)(Mg + (size_t)(16 * mt + fr) * 192 + 32 * ks + 8 * fq), xf[ks], acc);
; #pragma unroll
;                     for (int k4 = 0; k4 < 4; ++k4) acc = mfma16(mf[mt][k4], xhf[k4], acc);
;                     const int tok = (16 * nt + fr) * 4 + mt, ch = g * 16 + 4 * fq;
;                     const u32x2 uv = *(const u32x2*)(Zp + (size_t)tok * ZROWB + (C_S5U + ch) * 2);
;                     const float y0 = gelu_tanh(acc[0] + dsk[0] * bflo(uv.x)), y1 = gelu_tanh(acc[1] + dsk[1] * bfhi(uv.x));
;                     const float y2 = gelu_tanh(acc[2] + dsk[2] * bflo(uv.y)), y3 = gelu_tanh(acc[3] + dsk[3] * bfhi(uv.y));
;                     u32x2 w; w.x = pk2(y0, y1); w.y = pk2(y2, y3);
;                     *(u32x2*)(YS5 + (size_t)tok * 512 + ch * 2) = w;
	v_mfma_f32_16x16x32_bf16 v[162:165], v[78:81], v[158:161], v[162:165]
	s_nop 7
	v_fma_f32 v162, v130, v177, v162
	v_mul_f32_e32 v177, 0x3d372713, v162
	v_mul_f32_e32 v177, v162, v177
	v_fma_f32 v177, v162, v177, v162
	v_mul_f32_e32 v177, 0xc0135761, v177
	v_exp_f32_e32 v177, v177
	s_nop 0
	v_add_f32_e32 v177, 1.0, v177
	v_rcp_f32_e32 v177, v177
	s_nop 0
	v_mul_f32_e32 v162, v162, v177
	v_and_b32_e32 v177, 0xffff0000, v218
	v_fma_f32 v163, v131, v177, v163
	v_mul_f32_e32 v177, 0x3d372713, v163
	v_mul_f32_e32 v177, v163, v177
	v_fma_f32 v177, v163, v177, v163
	v_mul_f32_e32 v177, 0xc0135761, v177
	v_exp_f32_e32 v177, v177
	s_nop 0
	v_add_f32_e32 v177, 1.0, v177
	v_rcp_f32_e32 v177, v177
	s_nop 0
	v_mul_f32_e32 v163, v163, v177
	v_lshlrev_b32_e32 v177, 16, v219
	v_fma_f32 v164, v132, v177, v164
	v_mul_f32_e32 v177, 0x3d372713, v164
	v_mul_f32_e32 v177, v164, v177
	v_fma_f32 v177, v164, v177, v164
	v_mul_f32_e32 v177, 0xc0135761, v177
	v_exp_f32_e32 v177, v177
	v_cvt_pk_bf16_f32 v162, v162, v163
	s_nop 0
	v_add_f32_e32 v177, 1.0, v177
	v_rcp_f32_e32 v177, v177
	s_nop 0
	v_mul_f32_e32 v164, v164, v177
	v_and_b32_e32 v177, 0xffff0000, v219
	v_fmac_f32_e32 v165, v133, v177
	v_mul_f32_e32 v177, 0x3d372713, v165
	v_mul_f32_e32 v177, v165, v177
	v_fma_f32 v177, v165, v177, v165
	v_mul_f32_e32 v177, 0xc0135761, v177
	v_exp_f32_e32 v177, v177
	v_lshl_add_u64 v[216:217], v[212:213], 0, s[88:89]
	v_lshl_add_u64 v[212:213], v[212:213], 0, s[14:15]
	v_add_f32_e32 v177, 1.0, v177
	v_rcp_f32_e32 v177, v177
	s_nop 0
	v_mul_f32_e32 v165, v165, v177
	v_cvt_pk_bf16_f32 v163, v164, v165
	global_store_dwordx2 v[216:217], v[162:163], off offset:-1024
	v_mfma_f32_16x16x32_bf16 v[162:165], v[250:253], v[138:141], 0
	v_lshlrev_b32_e32 v177, 16, v224
	v_mfma_f32_16x16x32_bf16 v[162:165], v[82:85], v[146:149], v[162:165]
	v_mfma_f32_16x16x32_bf16 v[162:165], v[86:89], v[150:153], v[162:165]
	v_mfma_f32_16x16x32_bf16 v[162:165], v[90:93], v[154:157], v[162:165]
	v_mfma_f32_16x16x32_bf16 v[162:165], v[94:97], v[158:161], v[162:165]
	s_nop 7
	v_fma_f32 v162, v130, v177, v162
	v_mul_f32_e32 v177, 0x3d372713, v162
	v_mul_f32_e32 v177, v162, v177
	v_fma_f32 v177, v162, v177, v162
	v_mul_f32_e32 v177, 0xc0135761, v177
	v_exp_f32_e32 v177, v177
	s_nop 0
	v_add_f32_e32 v177, 1.0, v177
	v_rcp_f32_e32 v177, v177
	s_nop 0
	v_mul_f32_e32 v162, v162, v177
	v_and_b32_e32 v177, 0xffff0000, v224
	v_fma_f32 v163, v131, v177, v163
	v_mul_f32_e32 v177, 0x3d372713, v163
	v_mul_f32_e32 v177, v163, v177
	v_fma_f32 v177, v163, v177, v163
	v_mul_f32_e32 v177, 0xc0135761, v177
	v_exp_f32_e32 v177, v177
	s_nop 0
	v_add_f32_e32 v177, 1.0, v177
	v_rcp_f32_e32 v177, v177
	s_nop 0
	v_mul_f32_e32 v163, v163, v177
	v_lshlrev_b32_e32 v177, 16, v225
	v_fma_f32 v164, v132, v177, v164
	v_mul_f32_e32 v177, 0x3d372713, v164
	v_mul_f32_e32 v177, v164, v177
	v_fma_f32 v177, v164, v177, v164
	v_mul_f32_e32 v177, 0xc0135761, v177
	v_exp_f32_e32 v177, v177
	v_cvt_pk_bf16_f32 v162, v162, v163
	s_nop 0
	v_add_f32_e32 v177, 1.0, v177
	v_rcp_f32_e32 v177, v177
	s_nop 0
	v_mul_f32_e32 v164, v164, v177
	v_and_b32_e32 v177, 0xffff0000, v225
	v_fmac_f32_e32 v165, v133, v177
	v_mul_f32_e32 v177, 0x3d372713, v165
	v_mul_f32_e32 v177, v165, v177
	v_fma_f32 v177, v165, v177, v165
	v_mul_f32_e32 v177, 0xc0135761, v177
	v_exp_f32_e32 v177, v177
	s_nop 0
	v_add_f32_e32 v177, 1.0, v177
	v_rcp_f32_e32 v177, v177
	s_nop 0
	v_mul_f32_e32 v165, v165, v177
	v_cvt_pk_bf16_f32 v163, v164, v165
	global_store_dwordx2 v[216:217], v[162:163], off offset:-512
	ds_read_b128 v[162:165], v191
	s_nop 0
	ds_read_b128 v[244:247], v191 offset:8192
	s_waitcnt lgkmcnt(1)
	v_mfma_f32_16x16x32_bf16 v[162:165], v[162:165], v[138:141], 0
	s_waitcnt lgkmcnt(0)
	v_mfma_f32_16x16x32_bf16 v[162:165], v[244:247], v[142:145], v[162:165]
	v_mfma_f32_16x16x32_bf16 v[162:165], v[98:101], v[146:149], v[162:165]
	v_lshlrev_b32_e32 v177, 16, v254
	v_mfma_f32_16x16x32_bf16 v[162:165], v[102:105], v[150:153], v[162:165]
	v_mfma_f32_16x16x32_bf16 v[162:165], v[106:109], v[154:157], v[162:165]
	v_mfma_f32_16x16x32_bf16 v[162:165], v[110:113], v[158:161], v[162:165]
	s_nop 7
	v_fma_f32 v162, v130, v177, v162
	v_mul_f32_e32 v177, 0x3d372713, v162
	v_mul_f32_e32 v177, v162, v177
	v_fma_f32 v177, v162, v177, v162
	v_mul_f32_e32 v177, 0xc0135761, v177
	v_exp_f32_e32 v177, v177
	s_nop 0
	v_add_f32_e32 v177, 1.0, v177
	v_rcp_f32_e32 v177, v177
	s_nop 0
	v_mul_f32_e32 v162, v162, v177
	v_and_b32_e32 v177, 0xffff0000, v254
	v_fma_f32 v163, v131, v177, v163
	v_mul_f32_e32 v177, 0x3d372713, v163
	v_mul_f32_e32 v177, v163, v177
	v_fma_f32 v177, v163, v177, v163
	v_mul_f32_e32 v177, 0xc0135761, v177
	v_exp_f32_e32 v177, v177
	s_nop 0
	v_add_f32_e32 v177, 1.0, v177
	v_rcp_f32_e32 v177, v177
	s_nop 0
	v_mul_f32_e32 v163, v163, v177
	v_lshlrev_b32_e32 v177, 16, v255
	v_fma_f32 v164, v132, v177, v164
	v_mul_f32_e32 v177, 0x3d372713, v164
	v_mul_f32_e32 v177, v164, v177
	v_fma_f32 v177, v164, v177, v164
	v_mul_f32_e32 v177, 0xc0135761, v177
	v_exp_f32_e32 v177, v177
	v_cvt_pk_bf16_f32 v162, v162, v163
	s_nop 0
	v_add_f32_e32 v177, 1.0, v177
	v_rcp_f32_e32 v177, v177
	s_nop 0
	v_mul_f32_e32 v164, v164, v177
	v_and_b32_e32 v177, 0xffff0000, v255
	v_fmac_f32_e32 v165, v133, v177
	v_mul_f32_e32 v177, 0x3d372713, v165
	v_mul_f32_e32 v177, v165, v177
	v_fma_f32 v177, v165, v177, v165
	v_mul_f32_e32 v177, 0xc0135761, v177
	v_exp_f32_e32 v177, v177
	s_nop 0
	v_add_f32_e32 v177, 1.0, v177
	v_rcp_f32_e32 v177, v177
	s_nop 0
	v_mul_f32_e32 v165, v165, v177
	v_cvt_pk_bf16_f32 v163, v164, v165
	global_store_dwordx2 v[216:217], v[162:163], off
	ds_read_b128 v[162:165], v191 offset:16384
	s_waitcnt lgkmcnt(0)
; __device__ __forceinline__ unsigned pk2(float lo, float hi) { unsigned r; asm("v_cvt_pk_bf16_f32 %0, %1, %2" : "=v"(r) : "v"(lo), "v"(hi)); return r; }
; template <int PASS>
; __device__ __forceinline__ void s5_pass(CArgs& a, LAS unsigned char* lds, int l, int panel) {
;     ...
;         const int g = 2 * wave + gi;
;         const bf16_t* Wg = (const bf16_t*)(ws + WS_S5W) + (size_t)(l * 16 + g) * 128 * 64;
;         const bf16_t* Mg = (const bf16_t*)(ws + WS_S5M) + (size_t)(l * 16 + g) * 64 * 192;
;         bf16x8 wf[8][2];
; #pragma unroll
;         for (int mt = 0; mt < 8; ++mt)
; #pragma unroll
;             for (int ks = 0; ks < 2; ++ks) wf[mt][ks] = *(const bf16x8*)(Wg + (size_t)(16 * mt + fr) * 64 + 32 * ks + 8 * fq);
;         bf16x8 mf[4][4];
;         f32x4 dsk = (f32x4){0.f, 0.f, 0.f, 0.f};
;         if (PASS == 2) {
; #pragma unroll
;             for (int mt = 0; mt < 4; ++mt)
; #pragma unroll
;                 for (int ks = 0; ks < 4; ++ks) mf[mt][ks] = *(const bf16x8*)(Mg + (size_t)(16 * mt + fr) * 192 + 64 + 32 * ks + 8 * fq);
;             dsk = *(const f32x4*)(a.in[11] + l * 256 + g * 16 + 4 * fq);
;         }
;         const float* Ap = (const float*)(ws + WS_S5A) + ((size_t)(l * 16 + g) * 64 + lane) * 4;
;         const float a4r = Ap[0], a4i = Ap[1];
;         float* Hg = (float*)(ws + WS_S5H) + ((size_t)panel * 16 + g) * 128 + 2 * lane;
;         float Hr = 0.f, Hi = 0.f;
;         if (PASS == 2) { Hr = Hg[0]; Hi = Hg[1]; }
;     ...
;                     for (int ks = 0; ks < 2; ++ks) if (2 * ks <= mt) acc = mfma16(*(const bf16x8*)(Mg + (size_t)(16 * mt + fr) * 192 + 32 * ks + 8 * fq), xf[ks], acc);
; #pragma unroll
;                     for (int k4 = 0; k4 < 4; ++k4) acc = mfma16(mf[mt][k4], xhf[k4], acc);
;                     const int tok = (16 * nt + fr) * 4 + mt, ch = g * 16 + 4 * fq;
;                     const u32x2 uv = *(const u32x2*)(Zp + (size_t)tok * ZROWB + (C_S5U + ch) * 2);
;                     const float y0 = gelu_tanh(acc[0] + dsk[0] * bflo(uv.x)), y1 = gelu_tanh(acc[1] + dsk[1] * bfhi(uv.x));
;                     const float y2 = gelu_tanh(acc[2] + dsk[2] * bflo(uv.y)), y3 = gelu_tanh(acc[3] + dsk[3] * bfhi(uv.y));
;                     u32x2 w; w.x = pk2(y0, y1); w.y = pk2(y2, y3);
;                     *(u32x2*)(YS5 + (size_t)tok * 512 + ch * 2) = w;
;                 }
;             }
;             lds_fence();
;         }
	v_mfma_f32_16x16x32_bf16 v[138:141], v[162:165], v[138:141], 0
	ds_read_b128 v[162:165], v191 offset:24576
	s_waitcnt lgkmcnt(0)
	v_mfma_f32_16x16x32_bf16 v[138:141], v[162:165], v[142:145], v[138:141]
	v_mfma_f32_16x16x32_bf16 v[138:141], v[114:117], v[146:149], v[138:141]
	v_lshlrev_b32_e32 v144, 16, v223
	v_mfma_f32_16x16x32_bf16 v[138:141], v[118:121], v[150:153], v[138:141]
	v_and_b32_e32 v142, 0xffff0000, v223
	v_mfma_f32_16x16x32_bf16 v[138:141], v[122:125], v[154:157], v[138:141]
	v_mfma_f32_16x16x32_bf16 v[138:141], v[126:129], v[158:161], v[138:141]
	s_nop 7
	v_fma_f32 v139, v131, v142, v139
	v_mul_f32_e32 v142, 0x3d372713, v139
	v_mul_f32_e32 v142, v139, v142
	v_fma_f32 v142, v139, v142, v139
	v_mul_f32_e32 v142, 0xc0135761, v142
	v_exp_f32_e32 v142, v142
	v_fma_f32 v138, v130, v144, v138
	v_mul_f32_e32 v144, 0x3d372713, v138
	v_mul_f32_e32 v144, v138, v144
	v_add_f32_e32 v142, 1.0, v142
	v_rcp_f32_e32 v142, v142
	v_fma_f32 v144, v138, v144, v138
	v_mul_f32_e32 v144, 0x3f4c422a, v144
	v_mul_f32_e32 v144, -2.0, v144
	v_mul_f32_e32 v139, v139, v142
	v_lshlrev_b32_e32 v142, 16, v226
	v_fma_f32 v140, v132, v142, v140
	v_mul_f32_e32 v142, 0x3d372713, v140
	v_mul_f32_e32 v142, v140, v142
	v_fma_f32 v142, v140, v142, v140
	v_mul_f32_e32 v142, 0xc0135761, v142
	v_exp_f32_e32 v142, v142
	v_mul_f32_e32 v144, 0x3fb8aa3b, v144
	v_exp_f32_e32 v144, v144
	v_add_f32_e32 v142, 1.0, v142
	v_rcp_f32_e32 v142, v142
	v_add_f32_e32 v144, 1.0, v144
	v_rcp_f32_e32 v144, v144
	v_mul_f32_e32 v140, v140, v142
	v_and_b32_e32 v142, 0xffff0000, v226
	v_fmac_f32_e32 v141, v133, v142
	v_mul_f32_e32 v142, 0x3d372713, v141
	v_mul_f32_e32 v142, v141, v142
	v_fma_f32 v142, v141, v142, v141
	v_mul_f32_e32 v142, 0xc0135761, v142
	v_exp_f32_e32 v142, v142
	v_mul_f32_e32 v138, v138, v144
	v_cvt_pk_bf16_f32 v138, v138, v139
	v_add_f32_e32 v142, 1.0, v142
	v_rcp_f32_e32 v142, v142
	s_nop 0
	v_mul_f32_e32 v141, v141, v142
	v_cvt_pk_bf16_f32 v139, v140, v141
	global_store_dwordx2 v[216:217], v[138:139], off offset:512
	s_waitcnt lgkmcnt(0)
	s_cbranch_scc1 .LBB0_363
	s_or_b32 s10, s10, 1
	s_add_i32 s8, s10, s66
	s_ashr_i32 s9, s8, 31
	s_lshl_b64 s[18:19], s[8:9], 14
	s_mul_i32 s11, s8, 0x6000
	s_mul_hi_i32 s1, s8, 0x6000
	v_lshl_add_u64 v[58:59], v[174:175], 0, s[18:19]
	s_add_u32 s18, s4, s11
	s_addc_u32 s19, s5, s1
	v_lshlrev_b32_e32 v136, 1, v188
	v_mov_b32_e32 v137, v1
	v_lshl_add_u64 v[66:67], s[18:19], 0, v[136:137]
	v_lshlrev_b32_e32 v138, 1, v190
	v_mov_b32_e32 v139, v1
	v_lshl_add_u64 v[114:115], v[66:67], 0, v[138:139]
	s_mov_b64 s[4:5], 0x3000
	v_lshlrev_b32_e32 v2, 1, v172
	v_mov_b32_e32 v3, v1
	v_lshlrev_b32_e32 v18, 1, v176
	v_mov_b32_e32 v19, v1
	v_lshlrev_b32_e32 v26, 1, v178
	v_mov_b32_e32 v27, v1
	v_lshlrev_b32_e32 v34, 1, v180
	v_mov_b32_e32 v35, v1
	v_lshlrev_b32_e32 v42, 1, v182
	v_mov_b32_e32 v43, v1
	v_lshlrev_b32_e32 v50, 1, v184
	v_mov_b32_e32 v51, v1
	v_lshlrev_b32_e32 v60, 1, v186
	v_mov_b32_e32 v61, v1
	s_mov_b64 s[40:41], 0x1800
	v_lshl_add_u64 v[172:173], v[114:115], 0, s[4:5]
	s_lshl_b64 s[4:5], s[8:9], 10
	s_lshl_b32 s8, s10, 4
	s_ashr_i32 s11, s10, 31
	v_lshl_add_u64 v[14:15], v[58:59], 0, v[2:3]
	v_lshl_add_u64 v[22:23], v[58:59], 0, v[18:19]
	v_lshl_add_u64 v[30:31], v[58:59], 0, v[26:27]
	v_lshl_add_u64 v[38:39], v[58:59], 0, v[34:35]
	v_lshl_add_u64 v[46:47], v[58:59], 0, v[42:43]
	v_lshl_add_u64 v[54:55], v[58:59], 0, v[50:51]
	v_lshl_add_u64 v[62:63], v[58:59], 0, v[60:61]
	v_lshl_add_u64 v[94:95], v[114:115], 0, s[40:41]
	v_lshl_add_u64 v[116:117], v[170:171], 0, s[4:5]
	s_mov_b64 s[42:43], 0x4800
	s_ashr_i32 s9, s8, 31
	s_lshl_b64 s[4:5], s[10:11], 9
	global_load_dwordx4 v[2:5], v[14:15], off
	global_load_dwordx4 v[6:9], v[14:15], off offset:64
	global_load_dwordx4 v[10:13], v[14:15], off offset:2048
	s_nop 0
	global_load_dwordx4 v[14:17], v[14:15], off offset:2112
	s_nop 0
	global_load_dwordx4 v[18:21], v[22:23], off
	s_nop 0
	global_load_dwordx4 v[22:25], v[22:23], off offset:64
	s_nop 0
	global_load_dwordx4 v[26:29], v[30:31], off
	s_nop 0
	global_load_dwordx4 v[30:33], v[30:31], off offset:64
	s_nop 0
	global_load_dwordx4 v[34:37], v[38:39], off
	s_nop 0
	global_load_dwordx4 v[38:41], v[38:39], off offset:64
	s_nop 0
	global_load_dwordx4 v[42:45], v[46:47], off
	s_nop 0
	global_load_dwordx4 v[46:49], v[46:47], off offset:64
	s_nop 0
	global_load_dwordx4 v[50:53], v[54:55], off
	s_nop 0
	global_load_dwordx4 v[54:57], v[54:55], off offset:64
	s_nop 0
	global_load_dwordx4 v[58:61], v[62:63], off
	s_nop 0
	global_load_dwordx4 v[62:65], v[62:63], off offset:64
	s_nop 0
	global_load_dwordx4 v[66:69], v[114:115], off offset:128
	global_load_dwordx4 v[70:73], v[114:115], off offset:192
	global_load_dwordx4 v[74:77], v[114:115], off offset:256
	global_load_dwordx4 v[78:81], v[114:115], off offset:320
	global_load_dwordx4 v[82:85], v[94:95], off offset:128
	global_load_dwordx4 v[86:89], v[94:95], off offset:192
	global_load_dwordx4 v[90:93], v[94:95], off offset:256
	s_nop 0
	global_load_dwordx4 v[94:97], v[94:95], off offset:320
	s_nop 0
	global_load_dwordx4 v[98:101], v[172:173], off offset:128
	global_load_dwordx4 v[102:105], v[172:173], off offset:192
	global_load_dwordx4 v[106:109], v[172:173], off offset:256
	global_load_dwordx4 v[110:113], v[172:173], off offset:320
	v_lshl_add_u64 v[130:131], v[114:115], 0, s[42:43]
	v_lshl_add_u64 v[122:123], s[8:9], 2, v[166:167]
	v_lshl_add_u64 v[126:127], v[168:169], 0, s[4:5]
	global_load_dwordx2 v[170:171], v[116:117], off
	s_nop 0
	global_load_dwordx4 v[114:117], v[130:131], off offset:128
	global_load_dwordx4 v[118:121], v[130:131], off offset:192
	v_and_or_b32 v140, v190, 8, s8
	global_load_dwordx4 v[122:125], v[122:123], off
	s_nop 0
	global_load_dwordx2 v[134:135], v[126:127], off
	s_nop 0
	global_load_dwordx4 v[126:129], v[130:131], off offset:256
	s_nop 0
	global_load_dwordx4 v[130:133], v[130:131], off offset:320
	v_lshlrev_b32_e32 v140, 1, v140
	v_lshl_add_u64 v[138:139], s[18:19], 0, v[138:139]
	v_ashrrev_i32_e32 v141, 31, v140
	v_lshl_add_u64 v[168:169], v[138:139], 0, v[136:137]
	v_lshl_add_u64 v[136:137], v[140:141], 0, v[0:1]
	s_add_i32 s1, s26, 16
	v_lshl_add_u64 v[178:179], s[2:3], 0, v[136:137]
	v_add_lshl_u32 v136, s1, v181, 1
	v_ashrrev_i32_e32 v137, 31, v136
	v_lshl_add_u64 v[138:139], v[192:193], 0, v[136:137]
	v_lshl_add_u64 v[136:137], v[194:195], 0, v[136:137]
	s_mov_b32 s4, 4
	v_lshl_add_u64 v[174:175], v[168:169], 0, s[40:41]
	v_lshl_add_u64 v[176:177], v[168:169], 0, s[42:43]
	v_lshl_add_u64 v[180:181], s[2:3], 0, v[138:139]
	v_lshl_add_u64 v[182:183], s[38:39], 0, v[136:137]
	s_waitcnt vmcnt(6)
; #define LAS __attribute__((address_space(3)))
; __device__ __forceinline__ unsigned pk2(float lo, float hi) { unsigned r; asm("v_cvt_pk_bf16_f32 %0, %1, %2" : "=v"(r) : "v"(lo), "v"(hi)); return r; }
; __device__ __forceinline__ void lds_fence() { asm volatile("s_waitcnt lgkmcnt(0)" ::: "memory"); }
; __device__ __forceinline__ f32x4 mfma16(bf16x8 a, bf16x8 b, f32x4 c) { return __builtin_amdgcn_mfma_f32_16x16x32_bf16(a, b, c, 0, 0, 0); }
; template <int PASS>
; __device__ __forceinline__ void s5_pass(CArgs& a, LAS unsigned char* lds, int l, int panel) {
;     ...
;         for (int nt = 0; nt < 4; ++nt) {
;             bf16x8 xf[2];
; #pragma unroll
;             for (int ks = 0; ks < 2; ++ks) xf[ks] = *(const bf16x8*)(Zp + (size_t)(64 * nt + 4 * fr + 2 * ks + (fq >> 1)) * ZROWB + (C_S5U + g * 16 + (fq & 1) * 8) * 2);
; #pragma unroll
;             for (int mt = 0; mt < 8; ++mt) {
;                 f32x4 acc = mfma16(wf[mt][0], xf[0], (f32x4){0.f, 0.f, 0.f, 0.f});
;                 acc = mfma16(wf[mt][1], xf[1], acc);
;                 *(LAS f32x4*)(hl + fr * 128 + 16 * mt + 4 * fq) = acc;
;             }
;             lds_fence();
;             for (int j = 0; j < 16; ++j) {
;                 if (PASS == 2) *(LAS unsigned*)(xh + j * 128 + 2 * lane) = pk2(Hr, Hi);
;                 const f32x2 lc = *(LAS f32x2*)(hl + j * 128 + 2 * lane);
;                 const float nr = a4r * Hr - a4i * Hi + lc.x, ni = a4r * Hi + a4i * Hr + lc.y;
;                 Hr = nr; Hi = ni;
;             }
	v_pk_mov_b32 v[166:167], v[170:171], v[170:171] op_sel:[1,0]
	v_lshlrev_b32_e32 v191, 4, v189
	v_lshrrev_b32_e32 v223, 8, v189
	v_lshl_add_u32 v220, v223, 4, v191
	v_add_u32_e32 v220, 0x21000, v220
	v_add_u32_e32 v191, 0x18000, v191
	global_load_dwordx4 v[250:253], v[172:173], off
	global_load_dwordx4 v[162:165], v[172:173], off offset:64
	s_waitcnt vmcnt(0)
	ds_write_b128 v191, v[250:253]
	ds_write_b128 v191, v[162:165] offset:8192
	s_waitcnt lgkmcnt(0)
	global_load_dwordx4 v[250:253], v[176:177], off
	global_load_dwordx4 v[162:165], v[176:177], off offset:64
	s_waitcnt vmcnt(0)
	ds_write_b128 v191, v[250:253] offset:16384
	ds_write_b128 v191, v[162:165] offset:24576
	s_waitcnt lgkmcnt(0)
	global_load_dwordx4 v[162:165], v[168:169], off
	global_load_dwordx4 v[250:253], v[174:175], off
	s_waitcnt vmcnt(0)
	ds_write_b128 v220, v[162:165]
	s_waitcnt lgkmcnt(0)
.LBB0_365:
	v_lshl_add_u64 v[136:137], v[178:179], 0, s[88:89]
	v_add_co_u32_e32 v138, vcc, 0xe000000, v136
	s_waitcnt vmcnt(2)
	v_mul_f32_e32 v0, v171, v135
	v_addc_co_u32_e32 v139, vcc, 0, v137, vcc
	global_load_dwordx4 v[138:141], v[138:139], off
	v_add_co_u32_e32 v136, vcc, 0xe002000, v136
	v_cvt_pk_bf16_f32 v150, v134, v135
	v_lshl_add_u64 v[184:185], v[180:181], 0, s[88:89]
	s_nop 0
	v_addc_co_u32_e32 v137, vcc, 0, v137, vcc
	global_load_dwordx4 v[142:145], v[136:137], off offset:2048
	v_pk_fma_f32 v[136:137], v[170:171], v[134:135], v[0:1] op_sel_hi:[1,1,0] neg_lo:[0,0,1] neg_hi:[0,0,1]
	v_mul_f32_e32 v0, v167, v135
	v_pk_fma_f32 v[134:135], v[166:167], v[134:135], v[0:1] op_sel_hi:[1,1,0]
	v_add_co_u32_e32 v186, vcc, s20, v184
	s_add_i32 s4, s4, -1
	s_nop 0
	v_addc_co_u32_e32 v187, vcc, 0, v185, vcc
	v_add_co_u32_e32 v192, vcc, s95, v184
	v_lshl_add_u64 v[178:179], v[178:179], 0, s[82:83]
	s_nop 0
	v_addc_co_u32_e32 v193, vcc, 0, v185, vcc
	v_lshl_add_u64 v[180:181], v[180:181], 0, s[82:83]
	s_cmp_lg_u32 s4, 0
	global_load_dwordx2 v[218:219], v[186:187], off
	global_load_dwordx2 v[224:225], v[192:193], off offset:1024
	v_add_co_u32_e32 v194, vcc, s0, v184
	s_nop 1
	v_addc_co_u32_e32 v195, vcc, 0, v185, vcc
	global_load_dwordx2 v[254:255], v[194:195], off offset:2048
	v_add_co_u32_e32 v194, vcc, s96, v184
	s_nop 1
	v_addc_co_u32_e32 v195, vcc, 0, v185, vcc
	global_load_dword v223, v[194:195], off offset:3072
	global_load_dword v226, v[194:195], off offset:3076
	s_waitcnt vmcnt(6)
	v_mfma_f32_16x16x32_bf16 v[146:149], v[2:5], v[138:141], 0
	s_waitcnt vmcnt(5)
	v_mfma_f32_16x16x32_bf16 v[146:149], v[6:9], v[142:145], v[146:149]
	s_nop 7
	ds_write_b128 v238, v[146:149]
	v_mfma_f32_16x16x32_bf16 v[146:149], v[10:13], v[138:141], 0
	v_mfma_f32_16x16x32_bf16 v[146:149], v[14:17], v[142:145], v[146:149]
	s_nop 7
	ds_write_b128 v238, v[146:149] offset:64
	v_mfma_f32_16x16x32_bf16 v[146:149], v[18:21], v[138:141], 0
	v_mfma_f32_16x16x32_bf16 v[146:149], v[22:25], v[142:145], v[146:149]
	s_nop 7
	ds_write_b128 v238, v[146:149] offset:128
	v_mfma_f32_16x16x32_bf16 v[146:149], v[26:29], v[138:141], 0
	v_mfma_f32_16x16x32_bf16 v[146:149], v[30:33], v[142:145], v[146:149]
	s_nop 7
	ds_write_b128 v238, v[146:149] offset:192
	v_mfma_f32_16x16x32_bf16 v[146:149], v[34:37], v[138:141], 0
	v_mfma_f32_16x16x32_bf16 v[146:149], v[38:41], v[142:145], v[146:149]
	s_nop 7
	ds_write_b128 v238, v[146:149] offset:256
	v_mfma_f32_16x16x32_bf16 v[146:149], v[42:45], v[138:141], 0
	v_mfma_f32_16x16x32_bf16 v[146:149], v[46:49], v[142:145], v[146:149]
	s_nop 7
	ds_write_b128 v238, v[146:149] offset:320
	v_mfma_f32_16x16x32_bf16 v[146:149], v[50:53], v[138:141], 0
	v_mfma_f32_16x16x32_bf16 v[146:149], v[54:57], v[142:145], v[146:149]
	s_nop 7
	ds_write_b128 v238, v[146:149] offset:384
	v_mfma_f32_16x16x32_bf16 v[146:149], v[58:61], v[138:141], 0
	v_mfma_f32_16x16x32_bf16 v[146:149], v[62:65], v[142:145], v[146:149]
	s_nop 7
	ds_write_b128 v238, v[146:149] offset:448
	s_waitcnt lgkmcnt(0)
	ds_read2st64_b64 v[146:149], v241 offset1:1
	s_waitcnt lgkmcnt(0)
	v_pk_add_f32 v[134:135], v[134:135], v[146:147] op_sel:[0,1] op_sel_hi:[1,0]
	v_pk_add_f32 v[136:137], v[136:137], v[146:147]
	s_nop 0
	v_cvt_pk_bf16_f32 v0, v136, v134
	v_pk_mul_f32 v[134:135], v[166:167], v[134:135] op_sel_hi:[1,0]
	ds_write2st64_b32 v239, v150, v0 offset0:32 offset1:33
	v_pk_fma_f32 v[146:147], v[170:171], v[136:137], v[134:135] neg_lo:[0,0,1] neg_hi:[0,0,1]
	v_pk_fma_f32 v[134:135], v[170:171], v[136:137], v[134:135] op_sel_hi:[1,0,1]
	s_nop 0
	v_mov_b32_e32 v147, v135
	ds_read2st64_b64 v[134:137], v241 offset0:2 offset1:3
	v_pk_add_f32 v[146:147], v[146:147], v[148:149]
	s_nop 0
	v_mul_f32_e32 v0, v171, v147
	v_pk_fma_f32 v[148:149], v[170:171], v[146:147], v[0:1] op_sel_hi:[1,1,0] neg_lo:[0,0,1] neg_hi:[0,0,1]
	v_mul_f32_e32 v0, v171, v146
	v_cvt_pk_bf16_f32 v150, v146, v147
	v_pk_fma_f32 v[146:147], v[170:171], v[146:147], v[0:1] op_sel:[0,1,0] op_sel_hi:[1,0,0]
	s_waitcnt lgkmcnt(0)
	v_pk_add_f32 v[148:149], v[148:149], v[134:135]
	v_pk_add_f32 v[134:135], v[146:147], v[134:135] op_sel:[0,1] op_sel_hi:[1,0]
	s_nop 0
	v_cvt_pk_bf16_f32 v0, v148, v134
	v_pk_mul_f32 v[134:135], v[166:167], v[134:135] op_sel_hi:[1,0]
	ds_write2st64_b32 v239, v150, v0 offset0:34 offset1:35
	v_pk_fma_f32 v[146:147], v[170:171], v[148:149], v[134:135] neg_lo:[0,0,1] neg_hi:[0,0,1]
	v_pk_fma_f32 v[134:135], v[170:171], v[148:149], v[134:135] op_sel_hi:[1,0,1]
	s_nop 0
	v_mov_b32_e32 v147, v135
	v_pk_add_f32 v[146:147], v[146:147], v[136:137]
	ds_read2st64_b64 v[134:137], v241 offset0:4 offset1:5
	v_mul_f32_e32 v0, v171, v147
	v_pk_fma_f32 v[148:149], v[170:171], v[146:147], v[0:1] op_sel_hi:[1,1,0] neg_lo:[0,0,1] neg_hi:[0,0,1]
	v_mul_f32_e32 v0, v171, v146
	v_cvt_pk_bf16_f32 v150, v146, v147
	v_pk_fma_f32 v[146:147], v[170:171], v[146:147], v[0:1] op_sel:[0,1,0] op_sel_hi:[1,0,0]
	s_waitcnt lgkmcnt(0)
; #define LAS __attribute__((address_space(3)))
; __device__ __forceinline__ unsigned pk2(float lo, float hi) { unsigned r; asm("v_cvt_pk_bf16_f32 %0, %1, %2" : "=v"(r) : "v"(lo), "v"(hi)); return r; }
; __device__ __forceinline__ void lds_fence() { asm volatile("s_waitcnt lgkmcnt(0)" ::: "memory"); }
; __device__ __forceinline__ f32x4 mfma16(bf16x8 a, bf16x8 b, f32x4 c) { return __builtin_amdgcn_mfma_f32_16x16x32_bf16(a, b, c, 0, 0, 0); }
; template <int PASS>
; __device__ __forceinline__ void s5_pass(CArgs& a, LAS unsigned char* lds, int l, int panel) {
;     ...
;             for (int j = 0; j < 16; ++j) {
;                 if (PASS == 2) *(LAS unsigned*)(xh + j * 128 + 2 * lane) = pk2(Hr, Hi);
;                 const f32x2 lc = *(LAS f32x2*)(hl + j * 128 + 2 * lane);
;                 const float nr = a4r * Hr - a4i * Hi + lc.x, ni = a4r * Hi + a4i * Hr + lc.y;
;                 Hr = nr; Hi = ni;
;             }
;             lds_fence();
;             if (PASS == 2) {
;                 bf16x8 xhf[4];
; #pragma unroll
;                 for (int k4 = 0; k4 < 4; ++k4) xhf[k4] = *(const LAS bf16x8*)(xh + fr * 128 + 32 * k4 + 8 * fq);
; #pragma unroll
;                 for (int mt = 0; mt < 4; ++mt) {
;                     f32x4 acc = (f32x4){0.f, 0.f, 0.f, 0.f};
; #pragma unroll
;                     for (int ks = 0; ks < 2; ++ks) if (2 * ks <= mt) acc = mfma16(*(const bf16x8*)(Mg + (size_t)(16 * mt + fr) * 192 + 32 * ks + 8 * fq), xf[ks], acc);
; #pragma unroll
;                     for (int k4 = 0; k4 < 4; ++k4) acc = mfma16(mf[mt][k4], xhf[k4], acc);
	v_pk_add_f32 v[148:149], v[148:149], v[134:135]
	v_pk_add_f32 v[134:135], v[146:147], v[134:135] op_sel:[0,1] op_sel_hi:[1,0]
	s_nop 0
	v_cvt_pk_bf16_f32 v0, v148, v134
	v_pk_mul_f32 v[134:135], v[166:167], v[134:135] op_sel_hi:[1,0]
	ds_write2st64_b32 v239, v150, v0 offset0:36 offset1:37
	v_pk_fma_f32 v[146:147], v[170:171], v[148:149], v[134:135] neg_lo:[0,0,1] neg_hi:[0,0,1]
	v_pk_fma_f32 v[134:135], v[170:171], v[148:149], v[134:135] op_sel_hi:[1,0,1]
	s_nop 0
	v_mov_b32_e32 v147, v135
	v_pk_add_f32 v[146:147], v[146:147], v[136:137]
	ds_read2st64_b64 v[134:137], v241 offset0:6 offset1:7
	v_mul_f32_e32 v0, v171, v147
	v_pk_fma_f32 v[148:149], v[170:171], v[146:147], v[0:1] op_sel_hi:[1,1,0] neg_lo:[0,0,1] neg_hi:[0,0,1]
	v_mul_f32_e32 v0, v171, v146
	v_cvt_pk_bf16_f32 v150, v146, v147
	v_pk_fma_f32 v[146:147], v[170:171], v[146:147], v[0:1] op_sel:[0,1,0] op_sel_hi:[1,0,0]
	s_waitcnt lgkmcnt(0)
	v_pk_add_f32 v[148:149], v[148:149], v[134:135]
	v_pk_add_f32 v[134:135], v[146:147], v[134:135] op_sel:[0,1] op_sel_hi:[1,0]
	s_nop 0
	v_cvt_pk_bf16_f32 v0, v148, v134
	v_pk_mul_f32 v[134:135], v[166:167], v[134:135] op_sel_hi:[1,0]
	ds_write2st64_b32 v239, v150, v0 offset0:38 offset1:39
	v_pk_fma_f32 v[146:147], v[170:171], v[148:149], v[134:135] neg_lo:[0,0,1] neg_hi:[0,0,1]
	v_pk_fma_f32 v[134:135], v[170:171], v[148:149], v[134:135] op_sel_hi:[1,0,1]
	s_nop 0
	v_mov_b32_e32 v147, v135
	v_pk_add_f32 v[146:147], v[146:147], v[136:137]
	ds_read2st64_b64 v[134:137], v241 offset0:8 offset1:9
	v_mul_f32_e32 v0, v171, v147
	v_pk_fma_f32 v[148:149], v[170:171], v[146:147], v[0:1] op_sel_hi:[1,1,0] neg_lo:[0,0,1] neg_hi:[0,0,1]
	v_mul_f32_e32 v0, v171, v146
	v_cvt_pk_bf16_f32 v150, v146, v147
	v_pk_fma_f32 v[146:147], v[170:171], v[146:147], v[0:1] op_sel:[0,1,0] op_sel_hi:[1,0,0]
	s_waitcnt lgkmcnt(0)
	v_pk_add_f32 v[148:149], v[148:149], v[134:135]
	v_pk_add_f32 v[134:135], v[146:147], v[134:135] op_sel:[0,1] op_sel_hi:[1,0]
	s_nop 0
	v_cvt_pk_bf16_f32 v0, v148, v134
	v_pk_mul_f32 v[134:135], v[166:167], v[134:135] op_sel_hi:[1,0]
	ds_write2st64_b32 v239, v150, v0 offset0:40 offset1:41
	v_pk_fma_f32 v[146:147], v[170:171], v[148:149], v[134:135] neg_lo:[0,0,1] neg_hi:[0,0,1]
	v_pk_fma_f32 v[134:135], v[170:171], v[148:149], v[134:135] op_sel_hi:[1,0,1]
	s_nop 0
	v_mov_b32_e32 v147, v135
	v_pk_add_f32 v[146:147], v[146:147], v[136:137]
	ds_read2st64_b64 v[134:137], v241 offset0:10 offset1:11
	v_mul_f32_e32 v0, v171, v147
	v_pk_fma_f32 v[148:149], v[170:171], v[146:147], v[0:1] op_sel_hi:[1,1,0] neg_lo:[0,0,1] neg_hi:[0,0,1]
	v_mul_f32_e32 v0, v171, v146
	v_cvt_pk_bf16_f32 v150, v146, v147
	v_pk_fma_f32 v[146:147], v[170:171], v[146:147], v[0:1] op_sel:[0,1,0] op_sel_hi:[1,0,0]
	s_waitcnt lgkmcnt(0)
	v_pk_add_f32 v[148:149], v[148:149], v[134:135]
	v_pk_add_f32 v[134:135], v[146:147], v[134:135] op_sel:[0,1] op_sel_hi:[1,0]
	s_nop 0
	v_cvt_pk_bf16_f32 v0, v148, v134
	v_pk_mul_f32 v[134:135], v[170:171], v[134:135] op_sel_hi:[1,0]
	ds_write2st64_b32 v239, v150, v0 offset0:42 offset1:43
	v_pk_fma_f32 v[146:147], v[166:167], v[148:149], v[134:135]
	v_pk_fma_f32 v[134:135], v[166:167], v[148:149], v[134:135] op_sel_hi:[1,0,1] neg_lo:[0,0,1] neg_hi:[0,0,1]
	s_nop 0
	v_mov_b32_e32 v147, v135
	v_pk_add_f32 v[146:147], v[146:147], v[136:137] op_sel:[0,1] op_sel_hi:[1,0]
	ds_read2st64_b64 v[134:137], v241 offset0:12 offset1:13
	v_mul_f32_e32 v0, v171, v146
	v_pk_fma_f32 v[148:149], v[170:171], v[146:147], v[0:1] op_sel:[0,1,0] op_sel_hi:[1,0,0] neg_lo:[0,0,1] neg_hi:[0,0,1]
	v_mul_f32_e32 v0, v171, v147
	v_cvt_pk_bf16_f32 v150, v147, v146
	v_pk_fma_f32 v[146:147], v[170:171], v[146:147], v[0:1] op_sel_hi:[1,1,0]
	s_waitcnt lgkmcnt(0)
	v_pk_add_f32 v[148:149], v[148:149], v[134:135]
	v_pk_add_f32 v[134:135], v[146:147], v[134:135] op_sel:[0,1] op_sel_hi:[1,0]
	s_nop 0
	v_cvt_pk_bf16_f32 v0, v148, v134
	v_pk_mul_f32 v[134:135], v[170:171], v[134:135] op_sel_hi:[1,0]
	ds_write2st64_b32 v239, v150, v0 offset0:44 offset1:45
	v_pk_fma_f32 v[146:147], v[166:167], v[148:149], v[134:135]
	v_pk_fma_f32 v[134:135], v[166:167], v[148:149], v[134:135] op_sel_hi:[1,0,1] neg_lo:[0,0,1] neg_hi:[0,0,1]
	s_nop 0
	v_mov_b32_e32 v147, v135
	v_pk_add_f32 v[146:147], v[146:147], v[136:137] op_sel:[0,1] op_sel_hi:[1,0]
	ds_read2st64_b64 v[134:137], v241 offset0:14 offset1:15
	v_mul_f32_e32 v0, v171, v146
	v_pk_fma_f32 v[148:149], v[170:171], v[146:147], v[0:1] op_sel:[0,1,0] op_sel_hi:[1,0,0] neg_lo:[0,0,1] neg_hi:[0,0,1]
	v_mul_f32_e32 v0, v171, v147
	v_cvt_pk_bf16_f32 v150, v147, v146
	v_pk_fma_f32 v[146:147], v[170:171], v[146:147], v[0:1] op_sel_hi:[1,1,0]
	s_waitcnt lgkmcnt(0)
	v_pk_add_f32 v[162:163], v[148:149], v[134:135]
	v_pk_add_f32 v[134:135], v[146:147], v[134:135] op_sel:[0,1] op_sel_hi:[1,0]
	s_nop 0
	v_cvt_pk_bf16_f32 v0, v162, v134
	ds_write2st64_b32 v239, v150, v0 offset0:46 offset1:47
	v_pk_mul_f32 v[164:165], v[166:167], v[134:135] op_sel_hi:[1,0]
	s_waitcnt lgkmcnt(0)
	ds_read_b128 v[146:149], v240 offset:8192
	ds_read_b128 v[150:153], v240 offset:8256
	ds_read_b128 v[154:157], v240 offset:8320
	ds_read_b128 v[158:161], v240 offset:8384
	v_pk_fma_f32 v[134:135], v[170:171], v[162:163], v[164:165] neg_lo:[0,0,1] neg_hi:[0,0,1]
	v_pk_fma_f32 v[162:163], v[170:171], v[162:163], v[164:165] op_sel_hi:[1,0,1]
	v_mov_b32_e32 v135, v163
	ds_read_b128 v[162:165], v220
	s_waitcnt vmcnt(0) lgkmcnt(0)
	v_mfma_f32_16x16x32_bf16 v[162:165], v[162:165], v[138:141], 0
	v_lshlrev_b32_e32 v0, 16, v218
	v_pk_add_f32 v[134:135], v[134:135], v[136:137]
	s_waitcnt lgkmcnt(3)
	v_mfma_f32_16x16x32_bf16 v[162:165], v[66:69], v[146:149], v[162:165]
	s_waitcnt lgkmcnt(2)
; __device__ __forceinline__ unsigned pk2(float lo, float hi) { unsigned r; asm("v_cvt_pk_bf16_f32 %0, %1, %2" : "=v"(r) : "v"(lo), "v"(hi)); return r; }
; __device__ __forceinline__ float bflo(unsigned w) { return __uint_as_float(w << 16); }
; __device__ __forceinline__ float bfhi(unsigned w) { return __uint_as_float(w & 0xffff0000u); }
; __device__ __forceinline__ float gelu_tanh(float x) { const float u = 0.7978845608028654f * (x + 0.044715f * x * x * x); return x * __builtin_amdgcn_rcpf(1.f + fexp(-2.f * u)); }
; __device__ __forceinline__ f32x4 mfma16(bf16x8 a, bf16x8 b, f32x4 c) { return __builtin_amdgcn_mfma_f32_16x16x32_bf16(a, b, c, 0, 0, 0); }
; template <int PASS>
; __device__ __forceinline__ void s5_pass(CArgs& a, LAS unsigned char* lds, int l, int panel) {
;     ...
;                     for (int ks = 0; ks < 2; ++ks) if (2 * ks <= mt) acc = mfma16(*(const bf16x8*)(Mg + (size_t)(16 * mt + fr) * 192 + 32 * ks + 8 * fq), xf[ks], acc);
; #pragma unroll
;                     for (int k4 = 0; k4 < 4; ++k4) acc = mfma16(mf[mt][k4], xhf[k4], acc);
;                     const int tok = (16 * nt + fr) * 4 + mt, ch = g * 16 + 4 * fq;
;                     const u32x2 uv = *(const u32x2*)(Zp + (size_t)tok * ZROWB + (C_S5U + ch) * 2);
;                     const float y0 = gelu_tanh(acc[0] + dsk[0] * bflo(uv.x)), y1 = gelu_tanh(acc[1] + dsk[1] * bfhi(uv.x));
;                     const float y2 = gelu_tanh(acc[2] + dsk[2] * bflo(uv.y)), y3 = gelu_tanh(acc[3] + dsk[3] * bfhi(uv.y));
;                     u32x2 w; w.x = pk2(y0, y1); w.y = pk2(y2, y3);
;                     *(u32x2*)(YS5 + (size_t)tok * 512 + ch * 2) = w;
	v_mfma_f32_16x16x32_bf16 v[162:165], v[70:73], v[150:153], v[162:165]
	s_waitcnt lgkmcnt(1)
	v_mfma_f32_16x16x32_bf16 v[162:165], v[74:77], v[154:157], v[162:165]
	s_waitcnt lgkmcnt(0)
	v_mfma_f32_16x16x32_bf16 v[162:165], v[78:81], v[158:161], v[162:165]
	s_nop 7
	v_fma_f32 v0, v122, v0, v162
	v_mul_f32_e32 v162, 0x3d372713, v0
	v_mul_f32_e32 v162, v0, v162
	v_fma_f32 v162, v0, v162, v0
	v_mul_f32_e32 v162, 0xc0135761, v162
	v_exp_f32_e32 v162, v162
	s_nop 0
	v_add_f32_e32 v162, 1.0, v162
	v_rcp_f32_e32 v162, v162
	s_nop 0
	v_mul_f32_e32 v0, v0, v162
	v_and_b32_e32 v162, 0xffff0000, v218
	v_fma_f32 v162, v123, v162, v163
	v_mul_f32_e32 v163, 0x3d372713, v162
	v_mul_f32_e32 v163, v162, v163
	v_fma_f32 v163, v162, v163, v162
	v_mul_f32_e32 v163, 0xc0135761, v163
	v_exp_f32_e32 v163, v163
	s_nop 0
	v_add_f32_e32 v163, 1.0, v163
	v_rcp_f32_e32 v163, v163
	s_nop 0
	v_mul_f32_e32 v162, v162, v163
	v_lshlrev_b32_e32 v163, 16, v219
	v_fma_f32 v163, v124, v163, v164
	v_mul_f32_e32 v164, 0x3d372713, v163
	v_mul_f32_e32 v164, v163, v164
	v_fma_f32 v164, v163, v164, v163
	v_mul_f32_e32 v164, 0xc0135761, v164
	v_exp_f32_e32 v164, v164
	v_cvt_pk_bf16_f32 v162, v0, v162
	s_nop 0
	v_add_f32_e32 v164, 1.0, v164
	v_rcp_f32_e32 v164, v164
	s_nop 0
	v_mul_f32_e32 v163, v163, v164
	v_and_b32_e32 v164, 0xffff0000, v219
	v_fmac_f32_e32 v165, v125, v164
	v_mul_f32_e32 v164, 0x3d372713, v165
	v_mul_f32_e32 v164, v165, v164
	v_fma_f32 v164, v165, v164, v165
	v_mul_f32_e32 v164, 0xc0135761, v164
	v_exp_f32_e32 v164, v164
	v_lshl_add_u64 v[186:187], v[182:183], 0, s[88:89]
	v_lshl_add_u64 v[182:183], v[182:183], 0, s[14:15]
	v_add_f32_e32 v164, 1.0, v164
	v_rcp_f32_e32 v164, v164
	s_nop 0
	v_mul_f32_e32 v164, v165, v164
	v_cvt_pk_bf16_f32 v163, v163, v164
	global_store_dwordx2 v[186:187], v[162:163], off offset:-1024
	v_mfma_f32_16x16x32_bf16 v[162:165], v[250:253], v[138:141], 0
	v_lshlrev_b32_e32 v0, 16, v224
	v_mfma_f32_16x16x32_bf16 v[162:165], v[82:85], v[146:149], v[162:165]
	v_mfma_f32_16x16x32_bf16 v[162:165], v[86:89], v[150:153], v[162:165]
	v_mfma_f32_16x16x32_bf16 v[162:165], v[90:93], v[154:157], v[162:165]
	v_mfma_f32_16x16x32_bf16 v[162:165], v[94:97], v[158:161], v[162:165]
	s_nop 7
	v_fma_f32 v0, v122, v0, v162
	v_mul_f32_e32 v162, 0x3d372713, v0
	v_mul_f32_e32 v162, v0, v162
	v_fma_f32 v162, v0, v162, v0
	v_mul_f32_e32 v162, 0xc0135761, v162
	v_exp_f32_e32 v162, v162
	s_nop 0
	v_add_f32_e32 v162, 1.0, v162
	v_rcp_f32_e32 v162, v162
	s_nop 0
	v_mul_f32_e32 v0, v0, v162
	v_and_b32_e32 v162, 0xffff0000, v224
	v_fma_f32 v162, v123, v162, v163
	v_mul_f32_e32 v163, 0x3d372713, v162
	v_mul_f32_e32 v163, v162, v163
	v_fma_f32 v163, v162, v163, v162
	v_mul_f32_e32 v163, 0xc0135761, v163
	v_exp_f32_e32 v163, v163
	s_nop 0
	v_add_f32_e32 v163, 1.0, v163
	v_rcp_f32_e32 v163, v163
	s_nop 0
	v_mul_f32_e32 v162, v162, v163
	v_lshlrev_b32_e32 v163, 16, v225
	v_fma_f32 v163, v124, v163, v164
	v_mul_f32_e32 v164, 0x3d372713, v163
	v_mul_f32_e32 v164, v163, v164
	v_fma_f32 v164, v163, v164, v163
	v_mul_f32_e32 v164, 0xc0135761, v164
	v_exp_f32_e32 v164, v164
	v_cvt_pk_bf16_f32 v162, v0, v162
	s_nop 0
	v_add_f32_e32 v164, 1.0, v164
	v_rcp_f32_e32 v164, v164
	s_nop 0
	v_mul_f32_e32 v163, v163, v164
	v_and_b32_e32 v164, 0xffff0000, v225
	v_fmac_f32_e32 v165, v125, v164
	v_mul_f32_e32 v164, 0x3d372713, v165
	v_mul_f32_e32 v164, v165, v164
	v_fma_f32 v164, v165, v164, v165
	v_mul_f32_e32 v164, 0xc0135761, v164
	v_exp_f32_e32 v164, v164
	s_nop 0
	v_add_f32_e32 v164, 1.0, v164
	v_rcp_f32_e32 v164, v164
	s_nop 0
	v_mul_f32_e32 v164, v165, v164
	v_cvt_pk_bf16_f32 v163, v163, v164
	global_store_dwordx2 v[186:187], v[162:163], off offset:-512
	ds_read_b128 v[162:165], v191
	s_nop 0
	ds_read_b128 v[192:195], v191 offset:8192
	s_waitcnt lgkmcnt(1)
	v_mfma_f32_16x16x32_bf16 v[162:165], v[162:165], v[138:141], 0
	s_waitcnt lgkmcnt(0)
; __device__ __forceinline__ unsigned pk2(float lo, float hi) { unsigned r; asm("v_cvt_pk_bf16_f32 %0, %1, %2" : "=v"(r) : "v"(lo), "v"(hi)); return r; }
; __device__ __forceinline__ float bflo(unsigned w) { return __uint_as_float(w << 16); }
; __device__ __forceinline__ float bfhi(unsigned w) { return __uint_as_float(w & 0xffff0000u); }
; __device__ __forceinline__ float gelu_tanh(float x) { const float u = 0.7978845608028654f * (x + 0.044715f * x * x * x); return x * __builtin_amdgcn_rcpf(1.f + fexp(-2.f * u)); }
; __device__ __forceinline__ f32x4 mfma16(bf16x8 a, bf16x8 b, f32x4 c) { return __builtin_amdgcn_mfma_f32_16x16x32_bf16(a, b, c, 0, 0, 0); }
; template <int PASS>
; __device__ __forceinline__ void s5_pass(CArgs& a, LAS unsigned char* lds, int l, int panel) {
;     ...
;                     for (int ks = 0; ks < 2; ++ks) if (2 * ks <= mt) acc = mfma16(*(const bf16x8*)(Mg + (size_t)(16 * mt + fr) * 192 + 32 * ks + 8 * fq), xf[ks], acc);
; #pragma unroll
;                     for (int k4 = 0; k4 < 4; ++k4) acc = mfma16(mf[mt][k4], xhf[k4], acc);
;                     const int tok = (16 * nt + fr) * 4 + mt, ch = g * 16 + 4 * fq;
;                     const u32x2 uv = *(const u32x2*)(Zp + (size_t)tok * ZROWB + (C_S5U + ch) * 2);
;                     const float y0 = gelu_tanh(acc[0] + dsk[0] * bflo(uv.x)), y1 = gelu_tanh(acc[1] + dsk[1] * bfhi(uv.x));
;                     const float y2 = gelu_tanh(acc[2] + dsk[2] * bflo(uv.y)), y3 = gelu_tanh(acc[3] + dsk[3] * bfhi(uv.y));
;                     u32x2 w; w.x = pk2(y0, y1); w.y = pk2(y2, y3);
;                     *(u32x2*)(YS5 + (size_t)tok * 512 + ch * 2) = w;
; template <int PASS>
; __device__ __forceinline__ void gla_pass(CArgs& a, LAS unsigned char* lds, int l, int panel) {
;     ...
;     GLA_LOAD(0);
	v_mfma_f32_16x16x32_bf16 v[162:165], v[192:195], v[142:145], v[162:165]
	v_mfma_f32_16x16x32_bf16 v[162:165], v[98:101], v[146:149], v[162:165]
	v_lshlrev_b32_e32 v0, 16, v254
	v_mfma_f32_16x16x32_bf16 v[162:165], v[102:105], v[150:153], v[162:165]
	v_mfma_f32_16x16x32_bf16 v[162:165], v[106:109], v[154:157], v[162:165]
	v_mfma_f32_16x16x32_bf16 v[162:165], v[110:113], v[158:161], v[162:165]
	s_nop 7
	v_fma_f32 v0, v122, v0, v162
	v_mul_f32_e32 v162, 0x3d372713, v0
	v_mul_f32_e32 v162, v0, v162
	v_fma_f32 v162, v0, v162, v0
	v_mul_f32_e32 v162, 0xc0135761, v162
	v_exp_f32_e32 v162, v162
	s_nop 0
	v_add_f32_e32 v162, 1.0, v162
	v_rcp_f32_e32 v162, v162
	s_nop 0
	v_mul_f32_e32 v0, v0, v162
	v_and_b32_e32 v162, 0xffff0000, v254
	v_fma_f32 v162, v123, v162, v163
	v_mul_f32_e32 v163, 0x3d372713, v162
	v_mul_f32_e32 v163, v162, v163
	v_fma_f32 v163, v162, v163, v162
	v_mul_f32_e32 v163, 0xc0135761, v163
	v_exp_f32_e32 v163, v163
	s_nop 0
	v_add_f32_e32 v163, 1.0, v163
	v_rcp_f32_e32 v163, v163
	s_nop 0
	v_mul_f32_e32 v162, v162, v163
	v_lshlrev_b32_e32 v163, 16, v255
	v_fma_f32 v163, v124, v163, v164
	v_mul_f32_e32 v164, 0x3d372713, v163
	v_mul_f32_e32 v164, v163, v164
	v_fma_f32 v164, v163, v164, v163
	v_mul_f32_e32 v164, 0xc0135761, v164
	v_exp_f32_e32 v164, v164
	v_cvt_pk_bf16_f32 v162, v0, v162
	s_nop 0
	v_add_f32_e32 v164, 1.0, v164
	v_rcp_f32_e32 v164, v164
	s_nop 0
	v_mul_f32_e32 v163, v163, v164
	v_and_b32_e32 v164, 0xffff0000, v255
	v_fmac_f32_e32 v165, v125, v164
	v_mul_f32_e32 v164, 0x3d372713, v165
	v_mul_f32_e32 v164, v165, v164
	v_fma_f32 v164, v165, v164, v165
	v_mul_f32_e32 v164, 0xc0135761, v164
	v_exp_f32_e32 v164, v164
	s_nop 0
	v_add_f32_e32 v164, 1.0, v164
	v_rcp_f32_e32 v164, v164
	s_nop 0
	v_mul_f32_e32 v164, v165, v164
	v_cvt_pk_bf16_f32 v163, v163, v164
	global_store_dwordx2 v[186:187], v[162:163], off
	ds_read_b128 v[162:165], v191 offset:16384
	s_waitcnt lgkmcnt(0)
	v_mfma_f32_16x16x32_bf16 v[138:141], v[162:165], v[138:141], 0
	ds_read_b128 v[162:165], v191 offset:24576
	s_waitcnt lgkmcnt(0)
	v_mfma_f32_16x16x32_bf16 v[138:141], v[162:165], v[142:145], v[138:141]
	v_mfma_f32_16x16x32_bf16 v[138:141], v[114:117], v[146:149], v[138:141]
	v_lshlrev_b32_e32 v0, 16, v223
	v_mfma_f32_16x16x32_bf16 v[138:141], v[118:121], v[150:153], v[138:141]
	v_mfma_f32_16x16x32_bf16 v[138:141], v[126:129], v[154:157], v[138:141]
	v_mfma_f32_16x16x32_bf16 v[138:141], v[130:133], v[158:161], v[138:141]
	s_nop 7
	v_fma_f32 v0, v122, v0, v138
	v_mul_f32_e32 v138, 0x3d372713, v0
	v_mul_f32_e32 v138, v0, v138
	v_fma_f32 v138, v0, v138, v0
	v_mul_f32_e32 v138, 0xc0135761, v138
	v_exp_f32_e32 v138, v138
	s_nop 0
	v_add_f32_e32 v138, 1.0, v138
	v_rcp_f32_e32 v138, v138
	s_nop 0
	v_mul_f32_e32 v0, v0, v138
	v_and_b32_e32 v138, 0xffff0000, v223
	v_fma_f32 v138, v123, v138, v139
	v_mul_f32_e32 v139, 0x3d372713, v138
	v_mul_f32_e32 v139, v138, v139
	v_fma_f32 v139, v138, v139, v138
	v_mul_f32_e32 v139, 0xc0135761, v139
	v_exp_f32_e32 v139, v139
	s_nop 0
	v_add_f32_e32 v139, 1.0, v139
	v_rcp_f32_e32 v139, v139
	s_nop 0
	v_mul_f32_e32 v138, v138, v139
	v_lshlrev_b32_e32 v139, 16, v226
	v_fma_f32 v139, v124, v139, v140
	v_mul_f32_e32 v140, 0x3d372713, v139
	v_mul_f32_e32 v140, v139, v140
	v_fma_f32 v140, v139, v140, v139
	v_mul_f32_e32 v140, 0xc0135761, v140
	v_exp_f32_e32 v140, v140
	v_cvt_pk_bf16_f32 v138, v0, v138
	s_nop 0
	v_add_f32_e32 v140, 1.0, v140
	v_rcp_f32_e32 v140, v140
	s_nop 0
	v_mul_f32_e32 v139, v139, v140
	v_and_b32_e32 v140, 0xffff0000, v226
	v_fmac_f32_e32 v141, v125, v140
	v_mul_f32_e32 v140, 0x3d372713, v141
	v_mul_f32_e32 v140, v141, v140
	v_fma_f32 v140, v141, v140, v141
	v_mul_f32_e32 v140, 0xc0135761, v140
	v_exp_f32_e32 v140, v140
	s_nop 0
	v_add_f32_e32 v140, 1.0, v140
	v_rcp_f32_e32 v140, v140
	s_nop 0
	v_mul_f32_e32 v140, v141, v140
	v_cvt_pk_bf16_f32 v139, v139, v140
	global_store_dwordx2 v[186:187], v[138:139], off offset:512
	s_waitcnt lgkmcnt(0)
	s_cbranch_scc1 .LBB0_365
	v_readlane_b32 s38, v249, 0
	v_readlane_b32 s39, v249, 1
	v_mov_b32_e32 v10, v189
	s_barrier
	s_load_dwordx2 s[42:43], s[38:39], 0xf8
	v_ashrrev_i32_e32 v11, 8, v10
	v_mov_b32_e32 v20, v1
	v_mov_b32_e32 v21, v1
	v_and_b32_e32 v87, 63, v10
	s_waitcnt lgkmcnt(0)
	s_add_u32 s1, s42, s88
	s_addc_u32 s2, s43, s89
	s_add_u32 s26, s1, 0xe000000
	v_and_b32_e32 v86, 15, v10
	s_addc_u32 s27, s2, 0
	v_lshlrev_b32_e32 v144, 5, v11
	v_and_b32_e32 v88, 48, v10
	v_mov_b32_e32 v89, v1
	v_mov_b32_e32 v18, v1
	v_mov_b32_e32 v19, v1
	v_mov_b64_e32 v[24:25], v[20:21]
	v_cmp_gt_u32_e64 s[2:3], 32, v87
	v_or_b32_e32 v3, v144, v86
	v_lshl_add_u64 v[90:91], s[26:27], 0, v[88:89]
	v_mov_b64_e32 v[22:23], v[18:19]
	s_and_saveexec_b64 s[8:9], s[2:3]
	v_readlane_b32 s10, v248, 36
	v_readlane_b32 s11, v248, 37
	s_cbranch_execz .LBB0_368
	v_mad_i64_i32 v[4:5], s[4:5], v3, s90, v[90:91]
	v_add_co_u32_e32 v4, vcc, 0x1000, v4
	s_nop 1
	v_addc_co_u32_e32 v5, vcc, 0, v5, vcc
	global_load_dwordx4 v[22:25], v[4:5], off offset:512
